# phase0: x->bf16 loop loads batched + next-row prefetch; WA/WI gate-weight transposes spread over 16 WG groups
# speedup vs baseline: 1.0125x; 1.0125x over previous
;     const long total = (long)(K / 8) * Ndst;
; #pragma unroll 4
;     for (long it = gtid; it < total; it += gsz) {
;         const int n = (int)(it % Ndst), k8 = (int)(it / Ndst);
;         int sc = n;
;         if (MODE == 1) { if (n < 3584) sc = n; else sc = n + 16; }
;         u32x4 w = {0u, 0u, 0u, 0u};
;         if (sc >= 0) {
;             const float* s = src + (size_t)(k8 * 8) * Nsrc + sc;
; __device__ __forceinline__ void phase0(const Params& p) {
;     ...
;     for (int nb = 0; nb < 8; ++nb) {
;         transpose_w<0>(p.in[18] + nb * 192 * 192, 192, 192, (bf16_t*)(ws + WS_WA) + nb * 192 * 192, 192, nullptr, gtid, gsz, 1.4426950408889634f);
;         transpose_w<0>(p.in[20] + nb * 192 * 192, 192, 192, (bf16_t*)(ws + WS_WI) + nb * 192 * 192, 192, nullptr, gtid, gsz, 1.4426950408889634f);
;     }
.LBB0_37:
	s_or_b64 exec, exec, s[0:1]
	s_add_u32 s22, s44, 0x1900000
	s_addc_u32 s23, s45, 0
	s_mov_b64 s[10:11], 0x11ff
	s_add_u32 s24, s44, 0x1990000
	v_cmp_lt_u64_e32 vcc, s[10:11], v[8:9]
	s_addc_u32 s25, s45, 0
	s_mov_b32 s13, 0
	s_mov_b32 s26, 0xaaab
	s_movk_i32 s27, 0x300
	v_mov_b32_e32 v1, 0
	s_movk_i32 s28, 0x1000
	s_movk_i32 s29, 0x180
	s_mov_b32 s30, 0
	s_cmpk_eq_i32 s94, 0x100
	s_cbranch_scc1 .Lwawi_fast
	s_branch .LBB0_39

; __device__ __forceinline__ unsigned cvt_pk_bf16(float lo, float hi) { unsigned r; asm volatile("v_cvt_pk_bf16_f32 %0, %1, %2" : "=v"(r) : "v"(lo), "v"(hi)); return r; }
;     const long total = (long)(K / 8) * Ndst;
; #pragma unroll 4
;     for (long it = gtid; it < total; it += gsz) {
;         const int n = (int)(it % Ndst), k8 = (int)(it / Ndst);
;         int sc = n;
;         if (MODE == 1) { if (n < 3584) sc = n; else sc = n + 16; }
;         u32x4 w = {0u, 0u, 0u, 0u};
;         if (sc >= 0) {
;             const float* s = src + (size_t)(k8 * 8) * Nsrc + sc;
;             float v0 = s[0], v1 = s[(size_t)Nsrc], v2 = s[(size_t)2 * Nsrc], v3 = s[(size_t)3 * Nsrc], v4 = s[(size_t)4 * Nsrc], v5 = s[(size_t)5 * Nsrc], v6 = s[(size_t)6 * Nsrc], v7 = s[(size_t)7 * Nsrc];
;             if (gain) { const f32x4 g0 = *(const f32x4*)(gain + k8 * 8), g1 = *(const f32x4*)(gain + k8 * 8 + 4); v0 *= g0[0]; v1 *= g0[1]; v2 *= g0[2]; v3 *= g0[3]; v4 *= g1[0]; v5 *= g1[1]; v6 *= g1[2]; v7 *= g1[3]; }
;             w.x = cvt_pk_bf16(v0 * wscale, v1 * wscale); w.y = cvt_pk_bf16(v2 * wscale, v3 * wscale); w.z = cvt_pk_bf16(v4 * wscale, v5 * wscale); w.w = cvt_pk_bf16(v6 * wscale, v7 * wscale);
;         }
;         *(u32x4*)(dst + (size_t)n * K + k8 * 8) = w;
;     }
; }
; __device__ __forceinline__ void phase0(const Params& p) {
;     ...
;     for (int nb = 0; nb < 8; ++nb) {
;         transpose_w<0>(p.in[18] + nb * 192 * 192, 192, 192, (bf16_t*)(ws + WS_WA) + nb * 192 * 192, 192, nullptr, gtid, gsz, 1.4426950408889634f);
;         transpose_w<0>(p.in[20] + nb * 192 * 192, 192, 192, (bf16_t*)(ws + WS_WI) + nb * 192 * 192, 192, nullptr, gtid, gsz, 1.4426950408889634f);
;     }
.Lwawi_fast:
	s_and_b32 s0, s2, 15
	s_cmp_gt_u32 s0, 8
	s_cbranch_scc1 .LBB0_45
	s_lshl_b32 s0, s0, 9
	v_add_u32_e32 v6, s0, v136
	s_lshr_b32 s12, s2, 5
	s_mul_i32 s12, s12, 0x9000
	v_readlane_b32 s52, v250, 40
	v_readlane_b32 s53, v250, 41
	v_readlane_b32 s56, v250, 44
	v_readlane_b32 s57, v250, 45
	s_nop 1
	s_bitcmp1_b32 s2, 4
	s_cselect_b32 s0, s56, s52
	s_cselect_b32 s1, s57, s53
	s_cselect_b32 s14, 0x90000, 0
	s_add_i32 s14, s14, 0x1900000
	s_lshl_b64 s[16:17], s[12:13], 2
	s_add_u32 s0, s0, s16
	s_addc_u32 s1, s1, s17
	s_lshl_b32 s18, s12, 1
	s_add_u32 s34, s44, s14
	s_addc_u32 s35, s45, 0
	s_add_u32 s34, s34, s18
	s_addc_u32 s35, s35, 0
	v_mov_b64_e32 v[2:3], s[0:1]
	v_mov_b64_e32 v[4:5], s[34:35]
	v_mul_u32_u24_sdwa v0, v6, s26 dst_sel:DWORD dst_unused:UNUSED_PAD src0_sel:WORD_0 src1_sel:DWORD
	v_lshrrev_b32_e32 v0, 23, v0
	v_mul_lo_u16_e32 v12, 0xc0, v0
	v_lshlrev_b16_e32 v13, 3, v0
	v_sub_u16_e32 v12, v6, v12
	v_mad_u64_u32 v[10:11], s[0:1], v13, s27, v[2:3]
	v_lshlrev_b32_e32 v0, 2, v12
	v_lshl_add_u64 v[10:11], v[10:11], 0, v[0:1]
	global_load_dword v16, v[10:11], off
	global_load_dword v17, v[10:11], off offset:768
	global_load_dword v18, v[10:11], off offset:1536
	global_load_dword v19, v[10:11], off offset:2304
	global_load_dword v20, v[10:11], off offset:3072
	global_load_dword v21, v[10:11], off offset:3840
	v_add_co_u32_e64 v10, s[0:1], s28, v10
	s_nop 1
	v_addc_co_u32_e64 v11, s[0:1], 0, v11, s[0:1]
	global_load_dword v22, v[10:11], off offset:512
	global_load_dword v23, v[10:11], off offset:1280
	v_mad_u64_u32 v[10:11], s[0:1], v12, s29, v[4:5]
	v_lshlrev_b32_e32 v0, 1, v13
	v_lshl_add_u64 v[14:15], v[10:11], 0, v[0:1]
	s_waitcnt vmcnt(7)
	v_mul_f32_e32 v0, 0x3fb8aa3b, v16
	s_waitcnt vmcnt(6)
	v_mul_f32_e32 v10, 0x3fb8aa3b, v17
	s_waitcnt vmcnt(5)
	v_mul_f32_e32 v11, 0x3fb8aa3b, v18
	s_waitcnt vmcnt(4)
	v_mul_f32_e32 v12, 0x3fb8aa3b, v19
	s_waitcnt vmcnt(3)
	v_mul_f32_e32 v13, 0x3fb8aa3b, v20
	s_waitcnt vmcnt(2)
	v_mul_f32_e32 v16, 0x3fb8aa3b, v21
	v_cvt_pk_bf16_f32 v10, v0, v10
	v_cvt_pk_bf16_f32 v11, v11, v12
	v_cvt_pk_bf16_f32 v12, v13, v16
	s_waitcnt vmcnt(1)
	v_mul_f32_e32 v0, 0x3fb8aa3b, v22
	s_waitcnt vmcnt(0)
	v_mul_f32_e32 v13, 0x3fb8aa3b, v23
	v_cvt_pk_bf16_f32 v13, v0, v13
	global_store_dwordx4 v[14:15], v[10:13], off

; __device__ __forceinline__ void phase0(const Params& p) {
;     ...
;     const int lane = threadIdx.x & 63; const int gw = (int)(gtid >> 6), nw = (int)(gsz >> 6);
;     bf16_t* xb = (bf16_t*)(ws + WS_XB); float* rstd = (float*)(ws + WS_RSTD0);
; #pragma unroll 4
;     for (int row = gw; row < T; row += nw) {
;         const float* xr = (row < T_P) ? p.in[0] + (size_t)row * 1024 : p.in[1] + (size_t)(row - T_P) * 1024;
;         float ss = 0.f;
; #pragma unroll
;         for (int i = 0; i < 4; ++i) {
;             const f32x4 v = *(const f32x4*)(xr + i * 256 + lane * 4);
.LBB0_48:
	s_or_b64 exec, exec, s[0:1]
	v_lshrrev_b32_e32 v0, 6, v136
	v_and_b32_e32 v1, 63, v136
	s_lshl_b32 s8, s2, 3
	s_lshl_b32 s9, s94, 3
	v_readfirstlane_b32 s0, v0
	v_lshlrev_b32_e32 v2, 4, v1
	v_lshlrev_b32_e32 v3, 3, v1
	v_mbcnt_lo_u32_b32 v4, -1, 0
	s_add_i32 s8, s8, s0
	v_mbcnt_hi_u32_b32 v4, -1, v4
	v_cmp_eq_u32_e64 s[18:19], 0, v1
	v_xor_b32_e32 v16, 32, v4
	v_xor_b32_e32 v17, 16, v4
	v_xor_b32_e32 v18, 8, v4
	v_xor_b32_e32 v19, 4, v4
	v_xor_b32_e32 v20, 2, v4
	v_xor_b32_e32 v21, 1, v4
	v_lshlrev_b32_e32 v16, 2, v16
	v_lshlrev_b32_e32 v17, 2, v17
	v_lshlrev_b32_e32 v18, 2, v18
	v_lshlrev_b32_e32 v19, 2, v19
	v_lshlrev_b32_e32 v20, 2, v20
	v_lshlrev_b32_e32 v21, 2, v21
	v_mov_b32_e32 v22, 0x358637bd
	v_mov_b32_e32 v5, 0
	v_readlane_b32 s12, v250, 4
	v_readlane_b32 s13, v250, 5
	v_readlane_b32 s14, v250, 6
	v_readlane_b32 s15, v250, 7
	s_add_u32 s16, s44, 0x1a20000
	s_addc_u32 s17, s45, 0
	s_add_u32 s10, s44, 0x5e20000
	s_addc_u32 s11, s45, 0
	s_mov_b32 s27, 0x800000
	s_cmp_lt_i32 s8, 0x8800
	s_cbranch_scc0 .LBB0_55
	s_cmp_lt_i32 s8, 0x8000
	s_cselect_b32 s20, s12, s14
	s_cselect_b32 s21, s13, s15
	s_cselect_b32 s0, 0, 0x8000
	s_sub_i32 s0, s8, s0
	s_lshl_b32 s0, s0, 12
	s_add_u32 s20, s20, s0
	s_addc_u32 s21, s21, 0
	global_load_dwordx4 v[24:27], v2, s[20:21]
	global_load_dwordx4 v[28:31], v2, s[20:21] offset:1024
	global_load_dwordx4 v[32:35], v2, s[20:21] offset:2048
	global_load_dwordx4 v[36:39], v2, s[20:21] offset:3072
	s_waitcnt vmcnt(0)
	s_branch .Lxcv_a_ready

; __device__ __forceinline__ unsigned cvt_pk_bf16(float lo, float hi) { unsigned r; asm volatile("v_cvt_pk_bf16_f32 %0, %1, %2" : "=v"(r) : "v"(lo), "v"(hi)); return r; }
; __device__ __forceinline__ void phase0(const Params& p) {
;     ...
;     for (int row = gw; row < T; row += nw) {
;         const float* xr = (row < T_P) ? p.in[0] + (size_t)row * 1024 : p.in[1] + (size_t)(row - T_P) * 1024;
;         float ss = 0.f;
; #pragma unroll
;         for (int i = 0; i < 4; ++i) {
;             const f32x4 v = *(const f32x4*)(xr + i * 256 + lane * 4);
;             ss += v[0] * v[0] + v[1] * v[1] + v[2] * v[2] + v[3] * v[3];
;             u32x2 w; w.x = cvt_pk_bf16(v[0], v[1]); w.y = cvt_pk_bf16(v[2], v[3]);
;             *(u32x2*)(xb + (size_t)row * 1024 + i * 256 + lane * 4) = w;
;         }
; #pragma unroll
;         for (int o = 32; o >= 1; o >>= 1) ss += __shfl_xor(ss, o);
;         if (lane == 0) rstd[row] = rsqrtf(ss * (1.f / 1024.f) + EPS);
;     }
.Lxcv_a_ready:
	s_add_i32 s26, s8, s9
	s_cmp_lt_i32 s26, 0x8800
	s_cbranch_scc0 .Lxcv_a_nopf
	s_cmp_lt_i32 s26, 0x8000
	s_cselect_b32 s20, s12, s14
	s_cselect_b32 s21, s13, s15
	s_cselect_b32 s0, 0, 0x8000
	s_sub_i32 s0, s26, s0
	s_lshl_b32 s0, s0, 12
	s_add_u32 s20, s20, s0
	s_addc_u32 s21, s21, 0
	global_load_dwordx4 v[50:53], v2, s[20:21]
	global_load_dwordx4 v[54:57], v2, s[20:21] offset:1024
	global_load_dwordx4 v[58:61], v2, s[20:21] offset:2048
	global_load_dwordx4 v[62:65], v2, s[20:21] offset:3072
.Lxcv_a_nopf:
	s_lshl_b32 s0, s8, 11
	s_add_u32 s22, s16, s0
	s_addc_u32 s23, s17, 0
	v_cvt_pk_bf16_f32 v40, v24, v25
	v_cvt_pk_bf16_f32 v41, v26, v27
	v_cvt_pk_bf16_f32 v42, v28, v29
	v_cvt_pk_bf16_f32 v43, v30, v31
	v_cvt_pk_bf16_f32 v44, v32, v33
	v_cvt_pk_bf16_f32 v45, v34, v35
	v_cvt_pk_bf16_f32 v46, v36, v37
	v_cvt_pk_bf16_f32 v47, v38, v39
	global_store_dwordx2 v3, v[40:41], s[22:23]
	global_store_dwordx2 v3, v[42:43], s[22:23] offset:512
	global_store_dwordx2 v3, v[44:45], s[22:23] offset:1024
	global_store_dwordx2 v3, v[46:47], s[22:23] offset:1536
	v_mul_f32_e32 v12, v25, v25
	v_fmac_f32_e32 v12, v24, v24
	v_fmac_f32_e32 v12, v26, v26
	v_fmac_f32_e32 v12, v27, v27
	v_mul_f32_e32 v13, v29, v29
	v_fmac_f32_e32 v13, v28, v28
	v_fmac_f32_e32 v13, v30, v30
	v_fmac_f32_e32 v13, v31, v31
	v_add_f32_e32 v12, v12, v13
	v_mul_f32_e32 v13, v33, v33
	v_fmac_f32_e32 v13, v32, v32
	v_fmac_f32_e32 v13, v34, v34
	v_fmac_f32_e32 v13, v35, v35
	v_add_f32_e32 v12, v12, v13
	v_mul_f32_e32 v13, v37, v37
	v_fmac_f32_e32 v13, v36, v36
	v_fmac_f32_e32 v13, v38, v38
	v_fmac_f32_e32 v13, v39, v39
	v_add_f32_e32 v12, v12, v13
	ds_bpermute_b32 v13, v16, v12
	s_waitcnt lgkmcnt(0)
	v_add_f32_e32 v12, v12, v13
	ds_bpermute_b32 v13, v17, v12
	s_waitcnt lgkmcnt(0)
	v_add_f32_e32 v12, v12, v13
	ds_bpermute_b32 v13, v18, v12
	s_waitcnt lgkmcnt(0)
	v_add_f32_e32 v12, v12, v13
	ds_bpermute_b32 v13, v19, v12
	s_waitcnt lgkmcnt(0)
	v_add_f32_e32 v12, v12, v13
	ds_bpermute_b32 v13, v20, v12
	s_waitcnt lgkmcnt(0)
	v_add_f32_e32 v12, v12, v13
	ds_bpermute_b32 v13, v21, v12
	s_waitcnt lgkmcnt(0)
	v_add_f32_e32 v12, v12, v13
	v_fmamk_f32 v12, v12, 0x3a800000, v22
	v_mul_f32_e32 v13, 0x4b800000, v12
	v_cmp_gt_f32_e32 vcc, s27, v12
	s_lshl_b32 s0, s8, 2
	s_add_u32 s24, s10, s0
	v_cndmask_b32_e32 v12, v12, v13, vcc
	v_rsq_f32_e32 v12, v12
	s_addc_u32 s25, s11, 0
	v_mul_f32_e32 v13, 0x45800000, v12
	v_cndmask_b32_e32 v12, v12, v13, vcc
	s_mov_b64 exec, s[18:19]
	global_store_dword v5, v12, s[24:25]
	s_mov_b64 exec, -1
	s_mov_b32 s8, s26
	s_cmp_lt_i32 s8, 0x8800
	s_cbranch_scc0 .LBB0_55
	s_waitcnt vmcnt(5)
	s_add_i32 s26, s8, s9
	s_cmp_lt_i32 s26, 0x8800
	s_cbranch_scc0 .Lxcv_b_nopf
	s_cmp_lt_i32 s26, 0x8000
	s_cselect_b32 s20, s12, s14
	s_cselect_b32 s21, s13, s15
	s_cselect_b32 s0, 0, 0x8000
	s_sub_i32 s0, s26, s0
	s_lshl_b32 s0, s0, 12
	s_add_u32 s20, s20, s0
	s_addc_u32 s21, s21, 0
	global_load_dwordx4 v[24:27], v2, s[20:21]
	global_load_dwordx4 v[28:31], v2, s[20:21] offset:1024
	global_load_dwordx4 v[32:35], v2, s[20:21] offset:2048
	global_load_dwordx4 v[36:39], v2, s[20:21] offset:3072
.Lxcv_b_nopf:
	s_lshl_b32 s0, s8, 11
	s_add_u32 s22, s16, s0
	s_addc_u32 s23, s17, 0
	v_cvt_pk_bf16_f32 v66, v50, v51
	v_cvt_pk_bf16_f32 v67, v52, v53
	v_cvt_pk_bf16_f32 v68, v54, v55
	v_cvt_pk_bf16_f32 v69, v56, v57
	v_cvt_pk_bf16_f32 v70, v58, v59
	v_cvt_pk_bf16_f32 v71, v60, v61
	v_cvt_pk_bf16_f32 v72, v62, v63
	v_cvt_pk_bf16_f32 v73, v64, v65
	global_store_dwordx2 v3, v[66:67], s[22:23]
	global_store_dwordx2 v3, v[68:69], s[22:23] offset:512
	global_store_dwordx2 v3, v[70:71], s[22:23] offset:1024
	global_store_dwordx2 v3, v[72:73], s[22:23] offset:1536
	v_mul_f32_e32 v12, v51, v51
	v_fmac_f32_e32 v12, v50, v50
	v_fmac_f32_e32 v12, v52, v52
	v_fmac_f32_e32 v12, v53, v53
	v_mul_f32_e32 v13, v55, v55
	v_fmac_f32_e32 v13, v54, v54
	v_fmac_f32_e32 v13, v56, v56
	v_fmac_f32_e32 v13, v57, v57
	v_add_f32_e32 v12, v12, v13
	v_mul_f32_e32 v13, v59, v59
	v_fmac_f32_e32 v13, v58, v58
	v_fmac_f32_e32 v13, v60, v60
	v_fmac_f32_e32 v13, v61, v61
	v_add_f32_e32 v12, v12, v13
	v_mul_f32_e32 v13, v63, v63
	v_fmac_f32_e32 v13, v62, v62
	v_fmac_f32_e32 v13, v64, v64
	v_fmac_f32_e32 v13, v65, v65
	v_add_f32_e32 v12, v12, v13
	ds_bpermute_b32 v13, v16, v12
	s_waitcnt lgkmcnt(0)
	v_add_f32_e32 v12, v12, v13
	ds_bpermute_b32 v13, v17, v12
	s_waitcnt lgkmcnt(0)
	v_add_f32_e32 v12, v12, v13
	ds_bpermute_b32 v13, v18, v12
	s_waitcnt lgkmcnt(0)
	v_add_f32_e32 v12, v12, v13
	ds_bpermute_b32 v13, v19, v12
	s_waitcnt lgkmcnt(0)
	v_add_f32_e32 v12, v12, v13
	ds_bpermute_b32 v13, v20, v12
	s_waitcnt lgkmcnt(0)
	v_add_f32_e32 v12, v12, v13
	ds_bpermute_b32 v13, v21, v12
	s_waitcnt lgkmcnt(0)
	v_add_f32_e32 v12, v12, v13
	v_fmamk_f32 v12, v12, 0x3a800000, v22
	v_mul_f32_e32 v13, 0x4b800000, v12
	v_cmp_gt_f32_e32 vcc, s27, v12
	s_lshl_b32 s0, s8, 2
	s_add_u32 s24, s10, s0
	v_cndmask_b32_e32 v12, v12, v13, vcc
	v_rsq_f32_e32 v12, v12
	s_addc_u32 s25, s11, 0
	v_mul_f32_e32 v13, 0x45800000, v12
	v_cndmask_b32_e32 v12, v12, v13, vcc
	s_mov_b64 exec, s[18:19]
	global_store_dword v5, v12, s[24:25]
	s_mov_b64 exec, -1
	s_mov_b32 s8, s26
	s_cmp_lt_i32 s8, 0x8800
	s_cbranch_scc1 .Lxcv_loop
